# idle-slot filling: weight conversion of W1B, w_in, w_gate, w_branch, w_out moved from phase 0 into the idle tile slot of phase 1 (workgroups 128..239)
# speedup vs baseline: 1.0006x; 1.0006x over previous
; #define PH_BEGIN const int zi = opaque0(); unsigned char* ws = P.ws + zi; float* const OUT = P.out + zi; (void)OUT; const int tid = opqv((int)threadIdx.x); const int bid = opqs((int)blockIdx.x); const int G = opqs((int)gridDim.x); (void)tid; (void)bid; (void)G; unsigned char* WB = ws + WS_WB; float* SS = (float*)(ws + WS_SS); (void)WB; (void)SS; (void)zi;
; __global__ void __launch_bounds__(512) mega(Params P) {
;     ...
;             { PH_BEGIN convT_w<1>(INP(3) + (size_t)l * D * 2 * FF, 2 * FF, 0, INP(2) + (size_t)l * D, (bf16_t*)(WB + WB_W1A), D, D, 2 * FF, bid * 8 + (tid >> 6), G * 8, tid & 63, 0); }
;             { PH_BEGIN convT_w<0>(INP(4) + (size_t)l * FF * D, D, 0, nullptr, (bf16_t*)(WB + WB_W1B), FF, FF, D, bid * 8 + (tid >> 6), G * 8, tid & 63, 1408); }
;             { PH_BEGIN convT_w<2>(INP(7) + (size_t)l * D * 6928, 6928, 0, INP(5) + (size_t)l * D, (bf16_t*)(WB + WB_WIN), D, D, 4096, bid * 8 + (tid >> 6), G * 8, tid & 63, 2112); }
;             { PH_BEGIN convT_w<0>(INP(7) + (size_t)l * D * 6928, 6928, 3856, INP(5) + (size_t)l * D, (bf16_t*)(WB + WB_WG), D, D, 3072, bid * 8 + (tid >> 6), G * 8, tid & 63, 3136); }
;             for (int j = 0; j < 3; ++j) { PH_BEGIN convT_w<0>(INP(27) + ((size_t)l * 3 + j) * 512 * D, D, 0, nullptr, (bf16_t*)(WB + WB_WBR) + (size_t)j * D * 512, 512, 512, D, bid * 8 + (tid >> 6), G * 8, tid & 63, 3904 + 128 * j); }
;             { PH_BEGIN convT_w<0>(INP(28) + (size_t)l * D * D, D, 0, nullptr, (bf16_t*)(WB + WB_WO), D, D, D, bid * 8 + (tid >> 6), G * 8, tid & 63, 4288); }
;     ...
;         for (int rep = 0; rep < REPG; ++rep) {
;         { PH_BEGIN
;             pg8::Gemm g{XB_, (const bf16_t*)(WB + WB_W1A), T, 2 * FF, D, D, D, 0, 0}; pg8::StaticOrder S; S.init(T, 2 * FF, G, bid, 1);
;             EpiFFNa E{(bf16_t*)U_, SS + (size_t)0 * T * 16}; pg8::gemm_phase(lds, g, S, E, tid);
;         }
;         if ((int)blockIdx.x >= (int)gridDim.x - 16) { PH_BEGIN
;             pg8::Gemm g2{(const bf16_t*)(ws + WS_MEMN), (const bf16_t*)(WB + WB_WKV), 1024, D, D, D, D, 0, 0}; pg8::StaticOrder S2; S2.init(1024, D, 16, bid - (G - 16), 1);
;             EpiKV E2{KB_, VT_, (const float*)(ws + WS_MISC)}; pg8::gemm_phase(lds, g2, S2, E2, tid);
;         }
;         }
.LBB0_681:
	s_cmpk_lt_u32 s2, 0x80
	s_cbranch_scc1 .Lp1_noextra
	s_cmpk_gt_u32 s2, 0xef
	s_cbranch_scc1 .Lp1_noextra
	s_mul_i32 s1, s0, 0xab
	s_bfe_u32 s1, s1, 0x5000b
	s_and_b32 s16, s1, 0xffff
	s_lshl_b32 s19, s16, 10
	s_mov_b32 s28, 0xc000
	s_mov_b32 s29, 0xe000
	s_mov_b32 s72, 0xd000
	s_mov_b32 s73, 0x9000
	s_movk_i32 s74, 0x7000
	s_sub_i32 s2, s2, 0x80
	s_movk_i32 s3, 0x70
	s_branch .Lp0_mov_entry
.Lp1_back:
	s_add_i32 s2, s2, 0x80
	s_movk_i32 s3, 0x100

; #define PH_BEGIN const int zi = opaque0(); unsigned char* ws = P.ws + zi; float* const OUT = P.out + zi; (void)OUT; const int tid = opqv((int)threadIdx.x); const int bid = opqs((int)blockIdx.x); const int G = opqs((int)gridDim.x); (void)tid; (void)bid; (void)G; unsigned char* WB = ws + WS_WB; float* SS = (float*)(ws + WS_SS); (void)WB; (void)SS; (void)zi;
; template <int MAP>
; __device__ __forceinline__ void convT_w(const float* src, int ld, int coff, const float* g, bf16_t* dst, int K, int Kd, int Nd, int wslot, int nslots, int lane, int tile_base) {
;     const int nkt = K >> 4, nnt = (Nd + 255) >> 8, ntile = nkt * nnt;
;     for (int t = ((wslot - tile_base) % nslots + nslots) % nslots; t < ntile; t += nslots) {
;         const int kt = t % nkt, ntl = t / nkt, k0 = kt * 16, n = ntl * 256 + lane * 4; const int c = (n < Nd) ? colmap<MAP>(n) : -1;
;         const float* sp = src + (size_t)k0 * ld + coff + (c >= 0 ? c : 0);
; __global__ void __launch_bounds__(512) mega(Params P) {
;     ...
;             { PH_BEGIN convT_w<1>(INP(3) + (size_t)l * D * 2 * FF, 2 * FF, 0, INP(2) + (size_t)l * D, (bf16_t*)(WB + WB_W1A), D, D, 2 * FF, bid * 8 + (tid >> 6), G * 8, tid & 63, 0); }
;             { PH_BEGIN convT_w<0>(INP(4) + (size_t)l * FF * D, D, 0, nullptr, (bf16_t*)(WB + WB_W1B), FF, FF, D, bid * 8 + (tid >> 6), G * 8, tid & 63, 1408); }
.LBB0_690:
	s_or_b64 exec, exec, s[6:7]
	s_add_i32 s2, s2, 0x10000
	s_mov_b32 s3, 0x100000
.Lp0_mov_entry:
	s_mov_b32 s6, s63
	v_mov_b32_e32 v0, v232
	s_mov_b32 s4, s2
	s_mov_b32 s5, s3
	s_lshl_b32 s14, s5, 3
	s_abs_i32 s5, s14
	v_cvt_f32_u32_e32 v2, s5
	v_ashrrev_i32_e32 v3, 6, v0
	v_lshl_add_u32 v3, s4, 3, v3
	v_add_u32_e32 v3, 0xfffffa80, v3
	v_rcp_iflag_f32_e32 v2, v2
	v_sub_u32_e32 v5, 0, v3
	s_sub_i32 s4, 0, s5
	v_ashrrev_i32_e32 v4, 31, v3
	v_mul_f32_e32 v2, 0x4f7ffffe, v2
	v_cvt_u32_f32_e32 v2, v2
	v_max_i32_e32 v3, v3, v5
	s_mul_i32 s18, s16, 0x2c0000
	v_mul_lo_u32 v5, s4, v2
	v_mul_hi_u32 v5, v2, v5
	v_add_u32_e32 v2, v2, v5
	v_mul_hi_u32 v5, v3, v2
	v_mul_lo_u32 v5, v5, s5
	v_sub_u32_e32 v3, v3, v5
	v_subrev_u32_e32 v5, s5, v3
	v_cmp_le_u32_e32 vcc, s5, v3
	s_movk_i32 s4, 0x2c0
	s_nop 0
	v_cndmask_b32_e32 v3, v3, v5, vcc
	v_subrev_u32_e32 v5, s5, v3
	v_cmp_le_u32_e32 vcc, s5, v3
	s_nop 1
	v_cndmask_b32_e32 v3, v3, v5, vcc
	v_xor_b32_e32 v3, v3, v4
	v_sub_u32_e32 v3, v3, v4
	v_add_u32_e32 v3, s14, v3
	v_sub_u32_e32 v5, 0, v3
	v_ashrrev_i32_e32 v4, 31, v3
	v_max_i32_e32 v3, v3, v5
	v_mul_hi_u32 v2, v3, v2
	v_mul_lo_u32 v2, v2, s5
	v_sub_u32_e32 v2, v3, v2
	v_subrev_u32_e32 v3, s5, v2
	v_cmp_le_u32_e32 vcc, s5, v2
	s_nop 1
	v_cndmask_b32_e32 v2, v2, v3, vcc
	v_subrev_u32_e32 v3, s5, v2
	v_cmp_le_u32_e32 vcc, s5, v2
	s_nop 1
	v_cndmask_b32_e32 v2, v2, v3, vcc
	v_xor_b32_e32 v2, v2, v4
	v_sub_u32_e32 v3, v2, v4
	v_cmp_gt_i32_e32 vcc, s4, v3
	s_and_saveexec_b64 s[4:5], vcc
	s_cbranch_execz .LBB0_695
	v_readlane_b32 s44, v253, 21
	s_lshl_b32 s7, s18, 2
	v_readlane_b32 s52, v253, 29
	v_readlane_b32 s53, v253, 30
	s_add_u32 s8, s52, s7
	s_addc_u32 s9, s53, 0
	s_ashr_i32 s7, s6, 31
	s_add_u32 s10, s92, s6
	s_addc_u32 s11, s93, s7
	s_lshl_b64 s[6:7], s[6:7], 2
	s_add_u32 s6, s8, s6
	s_addc_u32 s7, s9, s7
	s_add_u32 s8, s10, 0xf00000
	v_lshlrev_b32_e32 v0, 2, v0
	s_addc_u32 s9, s11, 0
	v_and_b32_e32 v4, 0xfc, v0
	v_lshlrev_b32_e32 v2, 4, v3
	s_lshl_b32 s15, s14, 4
	s_mov_b64 s[10:11], 0
	v_readlane_b32 s45, v253, 22
	v_readlane_b32 s46, v253, 23
	v_readlane_b32 s47, v253, 24
	v_readlane_b32 s48, v253, 25
	v_readlane_b32 s49, v253, 26
	v_readlane_b32 s50, v253, 27
	v_readlane_b32 s51, v253, 28
	v_readlane_b32 s54, v253, 31
	v_readlane_b32 s55, v253, 32
	v_readlane_b32 s56, v253, 33
	v_readlane_b32 s57, v253, 34
	v_readlane_b32 s58, v253, 35
	v_readlane_b32 s59, v253, 36
	s_branch .LBB0_693

; #define PH_BEGIN const int zi = opaque0(); unsigned char* ws = P.ws + zi; float* const OUT = P.out + zi; (void)OUT; const int tid = opqv((int)threadIdx.x); const int bid = opqs((int)blockIdx.x); const int G = opqs((int)gridDim.x); (void)tid; (void)bid; (void)G; unsigned char* WB = ws + WS_WB; float* SS = (float*)(ws + WS_SS); (void)WB; (void)SS; (void)zi;
; template <int MAP>
; __device__ __forceinline__ void convT_w(const float* src, int ld, int coff, const float* g, bf16_t* dst, int K, int Kd, int Nd, int wslot, int nslots, int lane, int tile_base) {
;     const int nkt = K >> 4, nnt = (Nd + 255) >> 8, ntile = nkt * nnt;
;     for (int t = ((wslot - tile_base) % nslots + nslots) % nslots; t < ntile; t += nslots) {
;         const int kt = t % nkt, ntl = t / nkt, k0 = kt * 16, n = ntl * 256 + lane * 4; const int c = (n < Nd) ? colmap<MAP>(n) : -1;
;         const float* sp = src + (size_t)k0 * ld + coff + (c >= 0 ? c : 0);
; __global__ void __launch_bounds__(512) mega(Params P) {
;     ...
;             { PH_BEGIN convT_w<0>(INP(28) + (size_t)l * D * D, D, 0, nullptr, (bf16_t*)(WB + WB_WO), D, D, D, bid * 8 + (tid >> 6), G * 8, tid & 63, 4288); }
;             { PH_BEGIN convT_w<0>(INP(26) + (size_t)l * D * D, D, 0, INP(6) + (size_t)l * D, (bf16_t*)(WB + WB_WKV), D, D, D, bid * 8 + (tid >> 6), G * 8, tid & 63, 4544); }
.LBB0_720:
	s_or_b64 exec, exec, s[4:5]
	s_cmp_eq_u32 s3, 0x70
	s_cbranch_scc1 .Lp1_back
	s_sub_i32 s2, s2, 0x10000
	s_movk_i32 s3, 0x100
	s_mov_b32 s6, s63
	v_mov_b32_e32 v0, v232
	s_mov_b32 s4, s2
	s_mov_b32 s5, s3
	s_lshl_b32 s20, s5, 3
	s_abs_i32 s5, s20
	v_cvt_f32_u32_e32 v2, s5
	v_ashrrev_i32_e32 v3, 6, v0
	v_lshl_add_u32 v3, s4, 3, v3
	v_add_u32_e32 v3, 0xffffee40, v3
	v_rcp_iflag_f32_e32 v2, v2
	v_sub_u32_e32 v5, 0, v3
	s_sub_i32 s4, 0, s5
	v_ashrrev_i32_e32 v4, 31, v3
	v_mul_f32_e32 v2, 0x4f7ffffe, v2
	v_cvt_u32_f32_e32 v2, v2
	v_max_i32_e32 v3, v3, v5
	v_mul_lo_u32 v5, s4, v2
	v_mul_hi_u32 v5, v2, v5
	v_add_u32_e32 v2, v2, v5
	v_mul_hi_u32 v5, v3, v2
	v_mul_lo_u32 v5, v5, s5
	v_sub_u32_e32 v3, v3, v5
	v_subrev_u32_e32 v5, s5, v3
	v_cmp_le_u32_e32 vcc, s5, v3
	s_movk_i32 s4, 0x100
	s_nop 0
	v_cndmask_b32_e32 v3, v3, v5, vcc
	v_subrev_u32_e32 v5, s5, v3
	v_cmp_le_u32_e32 vcc, s5, v3
	s_nop 1
	v_cndmask_b32_e32 v3, v3, v5, vcc
	v_xor_b32_e32 v3, v3, v4
	v_sub_u32_e32 v3, v3, v4
	v_add_u32_e32 v3, s20, v3
	v_sub_u32_e32 v5, 0, v3
	v_ashrrev_i32_e32 v4, 31, v3
	v_max_i32_e32 v3, v3, v5
	v_mul_hi_u32 v2, v3, v2
	v_mul_lo_u32 v2, v2, s5
	v_sub_u32_e32 v2, v3, v2
	v_subrev_u32_e32 v3, s5, v2
	v_cmp_le_u32_e32 vcc, s5, v2
	s_nop 1
	v_cndmask_b32_e32 v2, v2, v3, vcc
	v_subrev_u32_e32 v3, s5, v2
	v_cmp_le_u32_e32 vcc, s5, v2
	s_nop 1
	v_cndmask_b32_e32 v2, v2, v3, vcc
	v_xor_b32_e32 v2, v2, v4
	v_sub_u32_e32 v22, v2, v4
	v_cmp_gt_i32_e32 vcc, s4, v22
	s_and_saveexec_b64 s[4:5], vcc
	s_cbranch_execz .LBB0_727
	v_readlane_b32 s36, v253, 39
	s_lshl_b32 s7, s14, 2
	v_readlane_b32 s40, v253, 43
	v_readlane_b32 s44, v253, 47
	v_readlane_b32 s45, v253, 48
	v_readlane_b32 s46, v253, 49
	v_readlane_b32 s47, v253, 50
	v_readlane_b32 s48, v253, 51
	v_readlane_b32 s49, v253, 52
	v_readlane_b32 s50, v253, 53
	v_readlane_b32 s51, v253, 54
	v_readlane_b32 s41, v253, 44
	s_add_u32 s10, s40, s7
	v_readlane_b32 s44, v253, 21
	s_addc_u32 s11, s41, 0
	v_readlane_b32 s56, v253, 33
	v_readlane_b32 s57, v253, 34
	s_add_u32 s12, s56, s19
	s_addc_u32 s13, s57, 0
	s_ashr_i32 s7, s6, 31
	s_add_u32 s14, s92, s6
	s_addc_u32 s15, s93, s7
	s_lshl_b64 s[8:9], s[6:7], 2
	s_add_u32 s6, s10, s8
	s_addc_u32 s7, s11, s9
	s_add_u32 s8, s12, s8
	s_addc_u32 s9, s13, s9
	v_readlane_b32 s59, v253, 36
	v_readlane_b32 s56, v255, 16
	s_add_u32 s10, s14, 0x2780000
	v_lshlrev_b32_e32 v0, 2, v0
	s_movk_i32 s59, 0x1ff
	v_readlane_b32 s57, v255, 17
	s_addc_u32 s11, s15, 0
	v_and_b32_e32 v23, 0xfc, v0
	v_lshlrev_b32_e32 v24, 4, v22
	s_lshl_b32 s21, s20, 4
	s_mov_b64 s[12:13], 0
	v_readlane_b32 s37, v253, 40
	v_readlane_b32 s38, v253, 41
	v_readlane_b32 s39, v253, 42
	v_readlane_b32 s42, v253, 45
	v_readlane_b32 s43, v253, 46
	v_readlane_b32 s45, v253, 22
	v_readlane_b32 s46, v253, 23
	v_readlane_b32 s47, v253, 24
	v_readlane_b32 s48, v253, 25
	v_readlane_b32 s49, v253, 26
	v_readlane_b32 s50, v253, 27
	v_readlane_b32 s51, v253, 28
	v_readlane_b32 s52, v253, 29
	v_readlane_b32 s53, v253, 30
	v_readlane_b32 s54, v253, 31
	v_readlane_b32 s55, v253, 32
	v_readlane_b32 s58, v253, 35
	s_branch .LBB0_724
